# baseline (speedup 1.0000x reference)
.LBB0_184:
	s_bfe_u32 s0, s13, 0x100005
	s_mulk_i32 s0, 0x2493
	s_lshr_b32 s0, s0, 16
	s_and_b32 s0, s0, 0xffff
	s_mul_i32 s2, s0, 0xff20
	s_add_i32 s3, s2, s13
	s_sext_i32_i16 s2, s3
	s_mulk_i32 s2, 0x4925
	s_lshr_b32 s4, s2, 31
	s_ashr_i32 s2, s2, 17
	s_add_i32 s2, s2, s4
	s_mul_i32 s4, s2, 7
	s_lshl_b32 s2, s2, 10
	s_or_b32 s2, s2, s14
	v_or_b32_e32 v2, s2, v1
	v_ashrrev_i32_e32 v3, 31, v2
	v_lshlrev_b64 v[2:3], 11, v[2:3]
	s_sub_i32 s3, s3, s4
	s_mul_i32 s0, s0, 7
	v_lshl_add_u64 v[104:105], v[100:101], 0, v[2:3]
	s_sext_i32_i16 s3, s3
	s_add_i32 s0, s0, s3
	s_lshl_b32 s3, s0, 7
	v_or_b32_e32 v18, s3, v1
	v_ashrrev_i32_e32 v19, 31, v18
	v_lshlrev_b64 v[18:19], 11, v[18:19]
	v_lshl_add_u64 v[108:109], v[102:103], 0, v[18:19]
	s_mov_b32 s4, -2
	s_mov_b32 s5, s1
	v_and_b32_e32 v181, 7, v106
	v_bfe_u32 v180, v106, 3, 3
	v_xor_b32_e32 v180, v181, v180
	v_sub_u32_e32 v180, v180, v181
	v_lshlrev_b32_e32 v180, 4, v180
	v_ashrrev_i32_e32 v181, 31, v180
	v_lshrrev_b32_e32 v186, 6, v106
	v_mov_b32_e32 v187, 0x110
	v_lshl_add_u32 v186, v186, 10, v187
	v_lshl_add_u64 v[188:189], v[104:105], 0, v[180:181]
	v_lshl_add_u64 v[196:197], v[108:109], 0, v[180:181]
	v_readfirstlane_b32 s6, v186
	v_add_co_u32_e32 v190, vcc, s15, v188
	v_addc_co_u32_e32 v191, vcc, 0, v189, vcc
	v_add_co_u32_e32 v192, vcc, s16, v188
	v_addc_co_u32_e32 v193, vcc, 0, v189, vcc
	v_add_co_u32_e32 v194, vcc, s17, v188
	v_addc_co_u32_e32 v195, vcc, 0, v189, vcc
	v_add_co_u32_e32 v198, vcc, s15, v196
	v_addc_co_u32_e32 v199, vcc, 0, v197, vcc
	v_add_co_u32_e32 v200, vcc, s16, v196
	v_addc_co_u32_e32 v201, vcc, 0, v197, vcc
	v_add_co_u32_e32 v202, vcc, s17, v196
	v_addc_co_u32_e32 v203, vcc, 0, v197, vcc
	s_add_u32 m0, s6, 0x0
	s_nop 0
	global_load_lds_dwordx4 v[188:189], off
	s_add_u32 m0, s6, 0x1000
	s_nop 0
	global_load_lds_dwordx4 v[190:191], off
	s_add_u32 m0, s6, 0x2000
	s_nop 0
	global_load_lds_dwordx4 v[192:193], off
	s_add_u32 m0, s6, 0x3000
	s_nop 0
	global_load_lds_dwordx4 v[194:195], off
	s_add_u32 m0, s6, 0x4000
	s_nop 0
	global_load_lds_dwordx4 v[196:197], off
	s_add_u32 m0, s6, 0x5000
	s_nop 0
	global_load_lds_dwordx4 v[198:199], off
	s_add_u32 m0, s6, 0x6000
	s_nop 0
	global_load_lds_dwordx4 v[200:201], off
	s_add_u32 m0, s6, 0x7000
	s_nop 0
	global_load_lds_dwordx4 v[202:203], off
	s_mov_b32 s0, 0x80
	s_add_u32 m0, s6, 0x8000
	v_lshl_add_u64 v[204:205], v[188:189], 0, s[0:1]
	global_load_lds_dwordx4 v[204:205], off
	s_add_u32 m0, s6, 0x9000
	v_lshl_add_u64 v[206:207], v[190:191], 0, s[0:1]
	global_load_lds_dwordx4 v[206:207], off
	s_add_u32 m0, s6, 0xa000
	v_lshl_add_u64 v[204:205], v[192:193], 0, s[0:1]
	global_load_lds_dwordx4 v[204:205], off
	s_add_u32 m0, s6, 0xb000
	v_lshl_add_u64 v[206:207], v[194:195], 0, s[0:1]
	global_load_lds_dwordx4 v[206:207], off
	s_add_u32 m0, s6, 0xc000
	v_lshl_add_u64 v[204:205], v[196:197], 0, s[0:1]
	global_load_lds_dwordx4 v[204:205], off
	s_add_u32 m0, s6, 0xd000
	v_lshl_add_u64 v[206:207], v[198:199], 0, s[0:1]
	global_load_lds_dwordx4 v[206:207], off
	s_add_u32 m0, s6, 0xe000
	v_lshl_add_u64 v[204:205], v[200:201], 0, s[0:1]
	global_load_lds_dwordx4 v[204:205], off
	s_add_u32 m0, s6, 0xf000
	v_lshl_add_u64 v[206:207], v[202:203], 0, s[0:1]
	global_load_lds_dwordx4 v[206:207], off
	s_mov_b32 s5, 0
	s_mov_b32 s4, 0
	v_mov_b32_e32 v26, 0
	v_mov_b32_e32 v27, v99
	v_mov_b32_e32 v28, v99
	v_mov_b32_e32 v29, v99
	v_mov_b32_e32 v46, 0
	v_mov_b32_e32 v47, v99
	v_mov_b32_e32 v48, v99
	v_mov_b32_e32 v49, v99
	v_mov_b32_e32 v62, 0
	v_mov_b32_e32 v63, v99
	v_mov_b32_e32 v64, v99
	v_mov_b32_e32 v65, v99
	v_mov_b32_e32 v78, 0
	v_mov_b32_e32 v79, v99
	v_mov_b32_e32 v80, v99
	v_mov_b32_e32 v81, v99
	v_mov_b32_e32 v82, 0
	v_mov_b32_e32 v83, v99
	v_mov_b32_e32 v84, v99
	v_mov_b32_e32 v85, v99
	v_mov_b32_e32 v86, 0
	v_mov_b32_e32 v87, v99
	v_mov_b32_e32 v88, v99
	v_mov_b32_e32 v89, v99
	v_mov_b32_e32 v90, 0
	v_mov_b32_e32 v91, v99
	v_mov_b32_e32 v92, v99
	v_mov_b32_e32 v93, v99
	v_mov_b32_e32 v94, 0
	v_mov_b32_e32 v95, v99
	v_mov_b32_e32 v96, v99
	v_mov_b32_e32 v97, v99
	v_mov_b32_e32 v38, 0
	v_mov_b32_e32 v39, v99
	v_mov_b32_e32 v40, v99
	v_mov_b32_e32 v41, v99
	v_mov_b32_e32 v30, 0
	v_mov_b32_e32 v31, v99
	v_mov_b32_e32 v32, v99
	v_mov_b32_e32 v33, v99
	v_mov_b32_e32 v22, 0
	v_mov_b32_e32 v23, v99
	v_mov_b32_e32 v24, v99
	v_mov_b32_e32 v25, v99
	v_mov_b32_e32 v18, 0
	v_mov_b32_e32 v19, v99
	v_mov_b32_e32 v20, v99
	v_mov_b32_e32 v21, v99
	v_mov_b32_e32 v14, 0
	v_mov_b32_e32 v15, v99
	v_mov_b32_e32 v16, v99
	v_mov_b32_e32 v17, v99
	v_mov_b32_e32 v10, 0
	v_mov_b32_e32 v11, v99
	v_mov_b32_e32 v12, v99
	v_mov_b32_e32 v13, v99
	v_mov_b32_e32 v6, 0
	v_mov_b32_e32 v7, v99
	v_mov_b32_e32 v8, v99
	v_mov_b32_e32 v9, v99
	v_mov_b32_e32 v2, 0
	v_mov_b32_e32 v3, v99
	v_mov_b32_e32 v4, v99
	v_mov_b32_e32 v5, v99
	s_waitcnt vmcnt(8)
	s_barrier

.LBB0_220:
	s_ashr_i32 s12, s2, 6
	s_ashr_i32 s13, s12, 31
	s_lshl_b64 s[16:17], s[12:13], 20
	s_add_u32 s18, s36, s16
	s_addc_u32 s19, s37, s17
	s_lshl_b32 s0, s2, 5
	s_and_b32 s16, s0, 0x780
	s_lshl_b32 s0, s2, 7
	s_and_b32 s17, s0, 0x180
	v_or_b32_e32 v2, s16, v1
	v_lshlrev_b32_e32 v98, 11, v2
	v_or_b32_e32 v2, s17, v1
	v_lshl_add_u64 v[104:105], v[100:101], 0, v[98:99]
	v_lshlrev_b32_e32 v98, 11, v2
	v_lshl_add_u64 v[2:3], s[18:19], 0, v[98:99]
	v_lshl_add_u64 v[108:109], v[2:3], 0, v[102:103]
	s_mov_b32 s18, -2
	s_mov_b32 s19, s1
	v_and_b32_e32 v181, 7, v106
	v_bfe_u32 v180, v106, 3, 3
	v_xor_b32_e32 v180, v181, v180
	v_sub_u32_e32 v180, v180, v181
	v_lshlrev_b32_e32 v180, 4, v180
	v_ashrrev_i32_e32 v181, 31, v180
	v_lshrrev_b32_e32 v186, 6, v106
	v_mov_b32_e32 v187, 0x110
	v_lshl_add_u32 v186, v186, 10, v187
	v_lshl_add_u64 v[188:189], v[104:105], 0, v[180:181]
	v_lshl_add_u64 v[196:197], v[108:109], 0, v[180:181]
	v_readfirstlane_b32 s20, v186
	v_add_co_u32_e32 v190, vcc, s3, v188
	v_addc_co_u32_e32 v191, vcc, 0, v189, vcc
	v_add_co_u32_e32 v192, vcc, s14, v188
	v_addc_co_u32_e32 v193, vcc, 0, v189, vcc
	v_add_co_u32_e32 v194, vcc, s15, v188
	v_addc_co_u32_e32 v195, vcc, 0, v189, vcc
	v_add_co_u32_e32 v198, vcc, s3, v196
	v_addc_co_u32_e32 v199, vcc, 0, v197, vcc
	v_add_co_u32_e32 v200, vcc, s14, v196
	v_addc_co_u32_e32 v201, vcc, 0, v197, vcc
	v_add_co_u32_e32 v202, vcc, s15, v196
	v_addc_co_u32_e32 v203, vcc, 0, v197, vcc
	s_add_u32 m0, s20, 0x0
	s_nop 0
	global_load_lds_dwordx4 v[188:189], off
	s_add_u32 m0, s20, 0x1000
	s_nop 0
	global_load_lds_dwordx4 v[190:191], off
	s_add_u32 m0, s20, 0x2000
	s_nop 0
	global_load_lds_dwordx4 v[192:193], off
	s_add_u32 m0, s20, 0x3000
	s_nop 0
	global_load_lds_dwordx4 v[194:195], off
	s_add_u32 m0, s20, 0x4000
	s_nop 0
	global_load_lds_dwordx4 v[196:197], off
	s_add_u32 m0, s20, 0x5000
	s_nop 0
	global_load_lds_dwordx4 v[198:199], off
	s_add_u32 m0, s20, 0x6000
	s_nop 0
	global_load_lds_dwordx4 v[200:201], off
	s_add_u32 m0, s20, 0x7000
	s_nop 0
	global_load_lds_dwordx4 v[202:203], off
	s_mov_b32 s0, 0x80
	s_add_u32 m0, s20, 0x8000
	v_lshl_add_u64 v[204:205], v[188:189], 0, s[0:1]
	global_load_lds_dwordx4 v[204:205], off
	s_add_u32 m0, s20, 0x9000
	v_lshl_add_u64 v[206:207], v[190:191], 0, s[0:1]
	global_load_lds_dwordx4 v[206:207], off
	s_add_u32 m0, s20, 0xa000
	v_lshl_add_u64 v[204:205], v[192:193], 0, s[0:1]
	global_load_lds_dwordx4 v[204:205], off
	s_add_u32 m0, s20, 0xb000
	v_lshl_add_u64 v[206:207], v[194:195], 0, s[0:1]
	global_load_lds_dwordx4 v[206:207], off
	s_add_u32 m0, s20, 0xc000
	v_lshl_add_u64 v[204:205], v[196:197], 0, s[0:1]
	global_load_lds_dwordx4 v[204:205], off
	s_add_u32 m0, s20, 0xd000
	v_lshl_add_u64 v[206:207], v[198:199], 0, s[0:1]
	global_load_lds_dwordx4 v[206:207], off
	s_add_u32 m0, s20, 0xe000
	v_lshl_add_u64 v[204:205], v[200:201], 0, s[0:1]
	global_load_lds_dwordx4 v[204:205], off
	s_add_u32 m0, s20, 0xf000
	v_lshl_add_u64 v[206:207], v[202:203], 0, s[0:1]
	global_load_lds_dwordx4 v[206:207], off
	s_mov_b32 s19, 0
	s_mov_b32 s18, 0
	v_mov_b32_e32 v34, 0
	v_mov_b32_e32 v35, v99
	v_mov_b32_e32 v36, v99
	v_mov_b32_e32 v37, v99
	v_mov_b32_e32 v38, 0
	v_mov_b32_e32 v39, v99
	v_mov_b32_e32 v40, v99
	v_mov_b32_e32 v41, v99
	v_mov_b32_e32 v54, 0
	v_mov_b32_e32 v55, v99
	v_mov_b32_e32 v56, v99
	v_mov_b32_e32 v57, v99
	v_mov_b32_e32 v78, 0
	v_mov_b32_e32 v79, v99
	v_mov_b32_e32 v80, v99
	v_mov_b32_e32 v81, v99
	v_mov_b32_e32 v82, 0
	v_mov_b32_e32 v83, v99
	v_mov_b32_e32 v84, v99
	v_mov_b32_e32 v85, v99
	v_mov_b32_e32 v86, 0
	v_mov_b32_e32 v87, v99
	v_mov_b32_e32 v88, v99
	v_mov_b32_e32 v89, v99
	v_mov_b32_e32 v90, 0
	v_mov_b32_e32 v91, v99
	v_mov_b32_e32 v92, v99
	v_mov_b32_e32 v93, v99
	v_mov_b32_e32 v94, 0
	v_mov_b32_e32 v95, v99
	v_mov_b32_e32 v96, v99
	v_mov_b32_e32 v97, v99
	v_mov_b32_e32 v74, 0
	v_mov_b32_e32 v75, v99
	v_mov_b32_e32 v76, v99
	v_mov_b32_e32 v77, v99
	v_mov_b32_e32 v70, 0
	v_mov_b32_e32 v71, v99
	v_mov_b32_e32 v72, v99
	v_mov_b32_e32 v73, v99
	v_mov_b32_e32 v66, 0
	v_mov_b32_e32 v67, v99
	v_mov_b32_e32 v68, v99
	v_mov_b32_e32 v69, v99
	v_mov_b32_e32 v62, 0
	v_mov_b32_e32 v63, v99
	v_mov_b32_e32 v64, v99
	v_mov_b32_e32 v65, v99
	v_mov_b32_e32 v58, 0
	v_mov_b32_e32 v59, v99
	v_mov_b32_e32 v60, v99
	v_mov_b32_e32 v61, v99
	v_mov_b32_e32 v50, 0
	v_mov_b32_e32 v51, v99
	v_mov_b32_e32 v52, v99
	v_mov_b32_e32 v53, v99
	v_mov_b32_e32 v46, 0
	v_mov_b32_e32 v47, v99
	v_mov_b32_e32 v48, v99
	v_mov_b32_e32 v49, v99
	v_mov_b32_e32 v42, 0
	v_mov_b32_e32 v43, v99
	v_mov_b32_e32 v44, v99
	v_mov_b32_e32 v45, v99
	s_waitcnt vmcnt(8)
	s_barrier

.LBB0_422:
	s_and_b32 s4, s7, 0xf8
	s_or_b32 s4, s4, s2
	s_lshl_b32 s11, s4, 7
	s_lshl_b32 s4, s7, 7
	v_or_b32_e32 v2, s11, v1
	s_and_b32 s12, s4, 0x380
	v_lshlrev_b32_e32 v98, 11, v2
	v_lshl_add_u64 v[104:105], v[102:103], 0, v[98:99]
	v_or_b32_e32 v2, s12, v1
	v_lshlrev_b32_e32 v98, 11, v2
	v_lshl_add_u64 v[108:109], v[100:101], 0, v[98:99]
	v_and_b32_e32 v177, 7, v106
	v_bfe_u32 v176, v106, 3, 3
	v_xor_b32_e32 v176, v177, v176
	v_sub_u32_e32 v176, v176, v177
	v_lshlrev_b32_e32 v176, 4, v176
	v_ashrrev_i32_e32 v177, 31, v176
	v_lshrrev_b32_e32 v182, 6, v106
	v_mov_b32_e32 v183, 0x110
	v_lshl_add_u32 v182, v182, 10, v183
	v_lshl_add_u64 v[184:185], v[104:105], 0, v[176:177]
	v_lshl_add_u64 v[192:193], v[108:109], 0, v[176:177]
	v_readfirstlane_b32 s15, v182
	v_add_co_u32_e32 v186, vcc, s8, v184
	v_addc_co_u32_e32 v187, vcc, 0, v185, vcc
	v_add_co_u32_e32 v188, vcc, s9, v184
	v_addc_co_u32_e32 v189, vcc, 0, v185, vcc
	v_add_co_u32_e32 v190, vcc, s10, v184
	v_addc_co_u32_e32 v191, vcc, 0, v185, vcc
	v_add_co_u32_e32 v194, vcc, s8, v192
	v_addc_co_u32_e32 v195, vcc, 0, v193, vcc
	v_add_co_u32_e32 v196, vcc, s9, v192
	v_addc_co_u32_e32 v197, vcc, 0, v193, vcc
	v_add_co_u32_e32 v198, vcc, s10, v192
	v_addc_co_u32_e32 v199, vcc, 0, v193, vcc
	s_add_u32 m0, s15, 0x0
	s_nop 0
	global_load_lds_dwordx4 v[184:185], off
	s_add_u32 m0, s15, 0x1000
	s_nop 0
	global_load_lds_dwordx4 v[186:187], off
	s_add_u32 m0, s15, 0x2000
	s_nop 0
	global_load_lds_dwordx4 v[188:189], off
	s_add_u32 m0, s15, 0x3000
	s_nop 0
	global_load_lds_dwordx4 v[190:191], off
	s_add_u32 m0, s15, 0x4000
	s_nop 0
	global_load_lds_dwordx4 v[192:193], off
	s_add_u32 m0, s15, 0x5000
	s_nop 0
	global_load_lds_dwordx4 v[194:195], off
	s_add_u32 m0, s15, 0x6000
	s_nop 0
	global_load_lds_dwordx4 v[196:197], off
	s_add_u32 m0, s15, 0x7000
	s_nop 0
	global_load_lds_dwordx4 v[198:199], off
	s_mov_b32 s4, 0x80
	s_add_u32 m0, s15, 0x8000
	v_lshl_add_u64 v[200:201], v[184:185], 0, s[4:5]
	global_load_lds_dwordx4 v[200:201], off
	s_add_u32 m0, s15, 0x9000
	v_lshl_add_u64 v[202:203], v[186:187], 0, s[4:5]
	global_load_lds_dwordx4 v[202:203], off
	s_add_u32 m0, s15, 0xa000
	v_lshl_add_u64 v[200:201], v[188:189], 0, s[4:5]
	global_load_lds_dwordx4 v[200:201], off
	s_add_u32 m0, s15, 0xb000
	v_lshl_add_u64 v[202:203], v[190:191], 0, s[4:5]
	global_load_lds_dwordx4 v[202:203], off
	s_add_u32 m0, s15, 0xc000
	v_lshl_add_u64 v[200:201], v[192:193], 0, s[4:5]
	global_load_lds_dwordx4 v[200:201], off
	s_add_u32 m0, s15, 0xd000
	v_lshl_add_u64 v[202:203], v[194:195], 0, s[4:5]
	global_load_lds_dwordx4 v[202:203], off
	s_add_u32 m0, s15, 0xe000
	v_lshl_add_u64 v[200:201], v[196:197], 0, s[4:5]
	global_load_lds_dwordx4 v[200:201], off
	s_add_u32 m0, s15, 0xf000
	v_lshl_add_u64 v[202:203], v[198:199], 0, s[4:5]
	global_load_lds_dwordx4 v[202:203], off
	s_mov_b32 s14, 0
	s_mov_b32 s13, 0
	v_mov_b32_e32 v30, 0
	v_mov_b32_e32 v31, v99
	v_mov_b32_e32 v32, v99
	v_mov_b32_e32 v33, v99
	v_mov_b32_e32 v62, 0
	v_mov_b32_e32 v63, v99
	v_mov_b32_e32 v64, v99
	v_mov_b32_e32 v65, v99
	v_mov_b32_e32 v74, 0
	v_mov_b32_e32 v75, v99
	v_mov_b32_e32 v76, v99
	v_mov_b32_e32 v77, v99
	v_mov_b32_e32 v78, 0
	v_mov_b32_e32 v79, v99
	v_mov_b32_e32 v80, v99
	v_mov_b32_e32 v81, v99
	v_mov_b32_e32 v82, 0
	v_mov_b32_e32 v83, v99
	v_mov_b32_e32 v84, v99
	v_mov_b32_e32 v85, v99
	v_mov_b32_e32 v86, 0
	v_mov_b32_e32 v87, v99
	v_mov_b32_e32 v88, v99
	v_mov_b32_e32 v89, v99
	v_mov_b32_e32 v90, 0
	v_mov_b32_e32 v91, v99
	v_mov_b32_e32 v92, v99
	v_mov_b32_e32 v93, v99
	v_mov_b32_e32 v94, 0
	v_mov_b32_e32 v95, v99
	v_mov_b32_e32 v96, v99
	v_mov_b32_e32 v97, v99
	v_mov_b32_e32 v66, 0
	v_mov_b32_e32 v67, v99
	v_mov_b32_e32 v68, v99
	v_mov_b32_e32 v69, v99
	v_mov_b32_e32 v38, 0
	v_mov_b32_e32 v39, v99
	v_mov_b32_e32 v40, v99
	v_mov_b32_e32 v41, v99
	v_mov_b32_e32 v34, 0
	v_mov_b32_e32 v35, v99
	v_mov_b32_e32 v36, v99
	v_mov_b32_e32 v37, v99
	v_mov_b32_e32 v18, 0
	v_mov_b32_e32 v19, v99
	v_mov_b32_e32 v20, v99
	v_mov_b32_e32 v21, v99
	v_mov_b32_e32 v14, 0
	v_mov_b32_e32 v15, v99
	v_mov_b32_e32 v16, v99
	v_mov_b32_e32 v17, v99
	v_mov_b32_e32 v10, 0
	v_mov_b32_e32 v11, v99
	v_mov_b32_e32 v12, v99
	v_mov_b32_e32 v13, v99
	v_mov_b32_e32 v6, 0
	v_mov_b32_e32 v7, v99
	v_mov_b32_e32 v8, v99
	v_mov_b32_e32 v9, v99
	v_mov_b32_e32 v2, 0
	v_mov_b32_e32 v3, v99
	v_mov_b32_e32 v4, v99
	v_mov_b32_e32 v5, v99
	s_waitcnt vmcnt(8)
	s_barrier

.LBB0_518:
	s_lshr_b32 s4, s6, 1
	s_and_b32 s4, s4, 0xf8
	s_or_b32 s4, s4, s2
	s_lshl_b32 s10, s4, 7
	s_lshl_b32 s4, s6, 7
	v_or_b32_e32 v2, s10, v1
	s_and_b32 s11, s4, 0x780
	v_lshlrev_b32_e32 v98, 10, v2
	v_lshl_add_u64 v[104:105], v[100:101], 0, v[98:99]
	v_or_b32_e32 v2, s11, v1
	v_lshlrev_b32_e32 v98, 10, v2
	v_lshl_add_u64 v[108:109], v[102:103], 0, v[98:99]
	v_and_b32_e32 v177, 7, v106
	v_bfe_u32 v176, v106, 3, 3
	v_xor_b32_e32 v176, v177, v176
	v_sub_u32_e32 v176, v176, v177
	v_lshlrev_b32_e32 v176, 4, v176
	v_ashrrev_i32_e32 v177, 31, v176
	v_lshrrev_b32_e32 v182, 6, v106
	v_mov_b32_e32 v183, 0x110
	v_lshl_add_u32 v182, v182, 10, v183
	v_lshl_add_u64 v[184:185], v[104:105], 0, v[176:177]
	v_lshl_add_u64 v[192:193], v[108:109], 0, v[176:177]
	v_readfirstlane_b32 s14, v182
	v_add_co_u32_e32 v186, vcc, s7, v184
	v_addc_co_u32_e32 v187, vcc, 0, v185, vcc
	v_add_co_u32_e32 v188, vcc, s8, v184
	v_addc_co_u32_e32 v189, vcc, 0, v185, vcc
	v_add_co_u32_e32 v190, vcc, s9, v184
	v_addc_co_u32_e32 v191, vcc, 0, v185, vcc
	v_add_co_u32_e32 v194, vcc, s7, v192
	v_addc_co_u32_e32 v195, vcc, 0, v193, vcc
	v_add_co_u32_e32 v196, vcc, s8, v192
	v_addc_co_u32_e32 v197, vcc, 0, v193, vcc
	v_add_co_u32_e32 v198, vcc, s9, v192
	v_addc_co_u32_e32 v199, vcc, 0, v193, vcc
	s_add_u32 m0, s14, 0x0
	s_nop 0
	global_load_lds_dwordx4 v[184:185], off
	s_add_u32 m0, s14, 0x1000
	s_nop 0
	global_load_lds_dwordx4 v[186:187], off
	s_add_u32 m0, s14, 0x2000
	s_nop 0
	global_load_lds_dwordx4 v[188:189], off
	s_add_u32 m0, s14, 0x3000
	s_nop 0
	global_load_lds_dwordx4 v[190:191], off
	s_add_u32 m0, s14, 0x4000
	s_nop 0
	global_load_lds_dwordx4 v[192:193], off
	s_add_u32 m0, s14, 0x5000
	s_nop 0
	global_load_lds_dwordx4 v[194:195], off
	s_add_u32 m0, s14, 0x6000
	s_nop 0
	global_load_lds_dwordx4 v[196:197], off
	s_add_u32 m0, s14, 0x7000
	s_nop 0
	global_load_lds_dwordx4 v[198:199], off
	s_mov_b32 s4, 0x80
	s_add_u32 m0, s14, 0x8000
	v_lshl_add_u64 v[200:201], v[184:185], 0, s[4:5]
	global_load_lds_dwordx4 v[200:201], off
	s_add_u32 m0, s14, 0x9000
	v_lshl_add_u64 v[202:203], v[186:187], 0, s[4:5]
	global_load_lds_dwordx4 v[202:203], off
	s_add_u32 m0, s14, 0xa000
	v_lshl_add_u64 v[200:201], v[188:189], 0, s[4:5]
	global_load_lds_dwordx4 v[200:201], off
	s_add_u32 m0, s14, 0xb000
	v_lshl_add_u64 v[202:203], v[190:191], 0, s[4:5]
	global_load_lds_dwordx4 v[202:203], off
	s_add_u32 m0, s14, 0xc000
	v_lshl_add_u64 v[200:201], v[192:193], 0, s[4:5]
	global_load_lds_dwordx4 v[200:201], off
	s_add_u32 m0, s14, 0xd000
	v_lshl_add_u64 v[202:203], v[194:195], 0, s[4:5]
	global_load_lds_dwordx4 v[202:203], off
	s_add_u32 m0, s14, 0xe000
	v_lshl_add_u64 v[200:201], v[196:197], 0, s[4:5]
	global_load_lds_dwordx4 v[200:201], off
	s_add_u32 m0, s14, 0xf000
	v_lshl_add_u64 v[202:203], v[198:199], 0, s[4:5]
	global_load_lds_dwordx4 v[202:203], off
	s_mov_b32 s13, 0
	s_mov_b32 s12, 0
	v_mov_b32_e32 v30, 0
	v_mov_b32_e32 v31, v99
	v_mov_b32_e32 v32, v99
	v_mov_b32_e32 v33, v99
	v_mov_b32_e32 v38, 0
	v_mov_b32_e32 v39, v99
	v_mov_b32_e32 v40, v99
	v_mov_b32_e32 v41, v99
	v_mov_b32_e32 v50, 0
	v_mov_b32_e32 v51, v99
	v_mov_b32_e32 v52, v99
	v_mov_b32_e32 v53, v99
	v_mov_b32_e32 v74, 0
	v_mov_b32_e32 v75, v99
	v_mov_b32_e32 v76, v99
	v_mov_b32_e32 v77, v99
	v_mov_b32_e32 v82, 0
	v_mov_b32_e32 v83, v99
	v_mov_b32_e32 v84, v99
	v_mov_b32_e32 v85, v99
	v_mov_b32_e32 v86, 0
	v_mov_b32_e32 v87, v99
	v_mov_b32_e32 v88, v99
	v_mov_b32_e32 v89, v99
	v_mov_b32_e32 v90, 0
	v_mov_b32_e32 v91, v99
	v_mov_b32_e32 v92, v99
	v_mov_b32_e32 v93, v99
	v_mov_b32_e32 v94, 0
	v_mov_b32_e32 v95, v99
	v_mov_b32_e32 v96, v99
	v_mov_b32_e32 v97, v99
	v_mov_b32_e32 v34, 0
	v_mov_b32_e32 v35, v99
	v_mov_b32_e32 v36, v99
	v_mov_b32_e32 v37, v99
	v_mov_b32_e32 v26, 0
	v_mov_b32_e32 v27, v99
	v_mov_b32_e32 v28, v99
	v_mov_b32_e32 v29, v99
	v_mov_b32_e32 v22, 0
	v_mov_b32_e32 v23, v99
	v_mov_b32_e32 v24, v99
	v_mov_b32_e32 v25, v99
	v_mov_b32_e32 v18, 0
	v_mov_b32_e32 v19, v99
	v_mov_b32_e32 v20, v99
	v_mov_b32_e32 v21, v99
	v_mov_b32_e32 v14, 0
	v_mov_b32_e32 v15, v99
	v_mov_b32_e32 v16, v99
	v_mov_b32_e32 v17, v99
	v_mov_b32_e32 v10, 0
	v_mov_b32_e32 v11, v99
	v_mov_b32_e32 v12, v99
	v_mov_b32_e32 v13, v99
	v_mov_b32_e32 v6, 0
	v_mov_b32_e32 v7, v99
	v_mov_b32_e32 v8, v99
	v_mov_b32_e32 v9, v99
	v_mov_b32_e32 v2, 0
	v_mov_b32_e32 v3, v99
	v_mov_b32_e32 v4, v99
	v_mov_b32_e32 v5, v99
	s_waitcnt vmcnt(8)
	s_barrier

.LBB0_664:
	s_cmpk_lt_u32 s3, 0x1c0
	s_cselect_b32 s4, 1, 2
	s_cselect_b32 s13, 7, 6
	s_cmpk_gt_u32 s3, 0xdf
	s_cselect_b32 s4, s4, 0
	s_mul_i32 s14, s4, 0xff20
	s_add_i32 s16, s14, s3
	s_sext_i32_i16 s14, s16
	v_cvt_f32_ubyte0_e32 v3, s13
	v_cvt_f32_i32_e32 v2, s14
	v_rcp_iflag_f32_e32 v4, v3
	s_ashr_i32 s14, s14, 30
	s_or_b32 s17, s14, 1
	s_mul_i32 s4, s4, 7
	v_mul_f32_e32 v4, v2, v4
	v_trunc_f32_e32 v4, v4
	v_fma_f32 v2, -v4, v3, v2
	v_cvt_i32_f32_e32 v4, v4
	v_cmp_ge_f32_e64 s[14:15], |v2|, v3
	s_and_b64 s[14:15], s[14:15], exec
	s_cselect_b32 s14, s17, 0
	v_readfirstlane_b32 s15, v4
	s_add_i32 s14, s15, s14
	s_sext_i32_i16 s15, s14
	s_mul_i32 s14, s14, s13
	s_sub_i32 s13, s16, s14
	s_sext_i32_i16 s13, s13
	s_add_i32 s4, s4, s13
	s_lshl_b32 s13, s15, 10
	s_or_b32 s13, s13, s6
	v_or_b32_e32 v2, s13, v1
	v_ashrrev_i32_e32 v3, 31, v2
	s_lshl_b32 s14, s4, 7
	v_lshlrev_b64 v[2:3], 12, v[2:3]
	v_lshl_add_u64 v[104:105], v[100:101], 0, v[2:3]
	v_or_b32_e32 v2, s14, v1
	v_ashrrev_i32_e32 v3, 31, v2
	v_lshlrev_b64 v[2:3], 11, v[2:3]
	v_add_co_u32_e32 v6, vcc, s7, v104
	v_lshl_add_u64 v[108:109], v[102:103], 0, v[2:3]
	v_and_b32_e32 v181, 7, v106
	v_bfe_u32 v180, v106, 3, 3
	v_xor_b32_e32 v180, v181, v180
	v_sub_u32_e32 v180, v180, v181
	v_lshlrev_b32_e32 v180, 4, v180
	v_ashrrev_i32_e32 v181, 31, v180
	v_lshrrev_b32_e32 v186, 6, v106
	v_mov_b32_e32 v187, 0x110
	v_lshl_add_u32 v186, v186, 10, v187
	v_lshl_add_u64 v[188:189], v[104:105], 0, v[180:181]
	v_lshl_add_u64 v[196:197], v[108:109], 0, v[180:181]
	v_readfirstlane_b32 s17, v186
	v_add_co_u32_e32 v190, vcc, s7, v188
	v_addc_co_u32_e32 v191, vcc, 0, v189, vcc
	v_add_co_u32_e32 v192, vcc, s9, v188
	v_addc_co_u32_e32 v193, vcc, 0, v189, vcc
	v_add_co_u32_e32 v194, vcc, s10, v188
	v_addc_co_u32_e32 v195, vcc, 0, v189, vcc
	v_add_co_u32_e32 v198, vcc, s8, v196
	v_addc_co_u32_e32 v199, vcc, 0, v197, vcc
	v_add_co_u32_e32 v200, vcc, s7, v196
	v_addc_co_u32_e32 v201, vcc, 0, v197, vcc
	v_add_co_u32_e32 v202, vcc, s11, v196
	v_addc_co_u32_e32 v203, vcc, 0, v197, vcc
	s_add_u32 m0, s17, 0x0
	s_nop 0
	global_load_lds_dwordx4 v[188:189], off
	s_add_u32 m0, s17, 0x1000
	s_nop 0
	global_load_lds_dwordx4 v[190:191], off
	s_add_u32 m0, s17, 0x2000
	s_nop 0
	global_load_lds_dwordx4 v[192:193], off
	s_add_u32 m0, s17, 0x3000
	s_nop 0
	global_load_lds_dwordx4 v[194:195], off
	s_add_u32 m0, s17, 0x4000
	s_nop 0
	global_load_lds_dwordx4 v[196:197], off
	s_add_u32 m0, s17, 0x5000
	s_nop 0
	global_load_lds_dwordx4 v[198:199], off
	s_add_u32 m0, s17, 0x6000
	s_nop 0
	global_load_lds_dwordx4 v[200:201], off
	s_add_u32 m0, s17, 0x7000
	s_nop 0
	global_load_lds_dwordx4 v[202:203], off
	s_mov_b32 s4, 0x80
	s_add_u32 m0, s17, 0x8000
	v_lshl_add_u64 v[204:205], v[188:189], 0, s[4:5]
	global_load_lds_dwordx4 v[204:205], off
	s_add_u32 m0, s17, 0x9000
	v_lshl_add_u64 v[206:207], v[190:191], 0, s[4:5]
	global_load_lds_dwordx4 v[206:207], off
	s_add_u32 m0, s17, 0xa000
	v_lshl_add_u64 v[204:205], v[192:193], 0, s[4:5]
	global_load_lds_dwordx4 v[204:205], off
	s_add_u32 m0, s17, 0xb000
	v_lshl_add_u64 v[206:207], v[194:195], 0, s[4:5]
	global_load_lds_dwordx4 v[206:207], off
	s_add_u32 m0, s17, 0xc000
	v_lshl_add_u64 v[204:205], v[196:197], 0, s[4:5]
	global_load_lds_dwordx4 v[204:205], off
	s_add_u32 m0, s17, 0xd000
	v_lshl_add_u64 v[206:207], v[198:199], 0, s[4:5]
	global_load_lds_dwordx4 v[206:207], off
	s_add_u32 m0, s17, 0xe000
	v_lshl_add_u64 v[204:205], v[200:201], 0, s[4:5]
	global_load_lds_dwordx4 v[204:205], off
	s_add_u32 m0, s17, 0xf000
	v_lshl_add_u64 v[206:207], v[202:203], 0, s[4:5]
	global_load_lds_dwordx4 v[206:207], off
	s_mov_b32 s16, 0
	s_mov_b32 s15, 0
	v_mov_b32_e32 v34, 0
	v_mov_b32_e32 v35, v99
	v_mov_b32_e32 v36, v99
	v_mov_b32_e32 v37, v99
	v_mov_b32_e32 v38, 0
	v_mov_b32_e32 v39, v99
	v_mov_b32_e32 v40, v99
	v_mov_b32_e32 v41, v99
	v_mov_b32_e32 v42, 0
	v_mov_b32_e32 v43, v99
	v_mov_b32_e32 v44, v99
	v_mov_b32_e32 v45, v99
	v_mov_b32_e32 v54, 0
	v_mov_b32_e32 v55, v99
	v_mov_b32_e32 v56, v99
	v_mov_b32_e32 v57, v99
	v_mov_b32_e32 v82, 0
	v_mov_b32_e32 v83, v99
	v_mov_b32_e32 v84, v99
	v_mov_b32_e32 v85, v99
	v_mov_b32_e32 v86, 0
	v_mov_b32_e32 v87, v99
	v_mov_b32_e32 v88, v99
	v_mov_b32_e32 v89, v99
	v_mov_b32_e32 v90, 0
	v_mov_b32_e32 v91, v99
	v_mov_b32_e32 v92, v99
	v_mov_b32_e32 v93, v99
	v_mov_b32_e32 v94, 0
	v_mov_b32_e32 v95, v99
	v_mov_b32_e32 v96, v99
	v_mov_b32_e32 v97, v99
	v_mov_b32_e32 v78, 0
	v_mov_b32_e32 v79, v99
	v_mov_b32_e32 v80, v99
	v_mov_b32_e32 v81, v99
	v_mov_b32_e32 v74, 0
	v_mov_b32_e32 v75, v99
	v_mov_b32_e32 v76, v99
	v_mov_b32_e32 v77, v99
	v_mov_b32_e32 v70, 0
	v_mov_b32_e32 v71, v99
	v_mov_b32_e32 v72, v99
	v_mov_b32_e32 v73, v99
	v_mov_b32_e32 v66, 0
	v_mov_b32_e32 v67, v99
	v_mov_b32_e32 v68, v99
	v_mov_b32_e32 v69, v99
	v_mov_b32_e32 v62, 0
	v_mov_b32_e32 v63, v99
	v_mov_b32_e32 v64, v99
	v_mov_b32_e32 v65, v99
	v_mov_b32_e32 v58, 0
	v_mov_b32_e32 v59, v99
	v_mov_b32_e32 v60, v99
	v_mov_b32_e32 v61, v99
	v_mov_b32_e32 v50, 0
	v_mov_b32_e32 v51, v99
	v_mov_b32_e32 v52, v99
	v_mov_b32_e32 v53, v99
	v_mov_b32_e32 v46, 0
	v_mov_b32_e32 v47, v99
	v_mov_b32_e32 v48, v99
	v_mov_b32_e32 v49, v99
	s_waitcnt vmcnt(8)
	s_barrier

.LBB0_798:
	s_and_b32 s4, s7, 0xf8
	s_or_b32 s4, s4, s2
	s_lshl_b32 s11, s4, 7
	s_lshl_b32 s4, s7, 7
	v_or_b32_e32 v0, s11, v107
	s_and_b32 s12, s4, 0x380
	v_lshlrev_b32_e32 v96, 11, v0
	v_lshl_add_u64 v[102:103], v[100:101], 0, v[96:97]
	v_or_b32_e32 v0, s12, v107
	v_lshlrev_b32_e32 v96, 11, v0
	v_lshl_add_u64 v[104:105], v[98:99], 0, v[96:97]
	v_and_b32_e32 v181, 7, v106
	v_bfe_u32 v180, v106, 3, 3
	v_xor_b32_e32 v180, v181, v180
	v_sub_u32_e32 v180, v180, v181
	v_lshlrev_b32_e32 v180, 4, v180
	v_ashrrev_i32_e32 v181, 31, v180
	v_lshrrev_b32_e32 v186, 6, v106
	v_mov_b32_e32 v187, 0x110
	v_lshl_add_u32 v186, v186, 10, v187
	v_lshl_add_u64 v[188:189], v[102:103], 0, v[180:181]
	v_lshl_add_u64 v[196:197], v[104:105], 0, v[180:181]
	v_readfirstlane_b32 s15, v186
	v_add_co_u32_e32 v190, vcc, s8, v188
	v_addc_co_u32_e32 v191, vcc, 0, v189, vcc
	v_add_co_u32_e32 v192, vcc, s9, v188
	v_addc_co_u32_e32 v193, vcc, 0, v189, vcc
	v_add_co_u32_e32 v194, vcc, s10, v188
	v_addc_co_u32_e32 v195, vcc, 0, v189, vcc
	v_add_co_u32_e32 v198, vcc, s8, v196
	v_addc_co_u32_e32 v199, vcc, 0, v197, vcc
	v_add_co_u32_e32 v200, vcc, s9, v196
	v_addc_co_u32_e32 v201, vcc, 0, v197, vcc
	v_add_co_u32_e32 v202, vcc, s10, v196
	v_addc_co_u32_e32 v203, vcc, 0, v197, vcc
	s_add_u32 m0, s15, 0x0
	s_nop 0
	global_load_lds_dwordx4 v[188:189], off
	s_add_u32 m0, s15, 0x1000
	s_nop 0
	global_load_lds_dwordx4 v[190:191], off
	s_add_u32 m0, s15, 0x2000
	s_nop 0
	global_load_lds_dwordx4 v[192:193], off
	s_add_u32 m0, s15, 0x3000
	s_nop 0
	global_load_lds_dwordx4 v[194:195], off
	s_add_u32 m0, s15, 0x4000
	s_nop 0
	global_load_lds_dwordx4 v[196:197], off
	s_add_u32 m0, s15, 0x5000
	s_nop 0
	global_load_lds_dwordx4 v[198:199], off
	s_add_u32 m0, s15, 0x6000
	s_nop 0
	global_load_lds_dwordx4 v[200:201], off
	s_add_u32 m0, s15, 0x7000
	s_nop 0
	global_load_lds_dwordx4 v[202:203], off
	s_mov_b32 s4, 0x80
	s_add_u32 m0, s15, 0x8000
	v_lshl_add_u64 v[204:205], v[188:189], 0, s[4:5]
	global_load_lds_dwordx4 v[204:205], off
	s_add_u32 m0, s15, 0x9000
	v_lshl_add_u64 v[206:207], v[190:191], 0, s[4:5]
	global_load_lds_dwordx4 v[206:207], off
	s_add_u32 m0, s15, 0xa000
	v_lshl_add_u64 v[204:205], v[192:193], 0, s[4:5]
	global_load_lds_dwordx4 v[204:205], off
	s_add_u32 m0, s15, 0xb000
	v_lshl_add_u64 v[206:207], v[194:195], 0, s[4:5]
	global_load_lds_dwordx4 v[206:207], off
	s_add_u32 m0, s15, 0xc000
	v_lshl_add_u64 v[204:205], v[196:197], 0, s[4:5]
	global_load_lds_dwordx4 v[204:205], off
	s_add_u32 m0, s15, 0xd000
	v_lshl_add_u64 v[206:207], v[198:199], 0, s[4:5]
	global_load_lds_dwordx4 v[206:207], off
	s_add_u32 m0, s15, 0xe000
	v_lshl_add_u64 v[204:205], v[200:201], 0, s[4:5]
	global_load_lds_dwordx4 v[204:205], off
	s_add_u32 m0, s15, 0xf000
	v_lshl_add_u64 v[206:207], v[202:203], 0, s[4:5]
	global_load_lds_dwordx4 v[206:207], off
	s_mov_b32 s14, 0
	s_mov_b32 s13, 0
	v_mov_b32_e32 v28, 0
	v_mov_b32_e32 v29, v97
	v_mov_b32_e32 v30, v97
	v_mov_b32_e32 v31, v97
	v_mov_b32_e32 v60, 0
	v_mov_b32_e32 v61, v97
	v_mov_b32_e32 v62, v97
	v_mov_b32_e32 v63, v97
	v_mov_b32_e32 v72, 0
	v_mov_b32_e32 v73, v97
	v_mov_b32_e32 v74, v97
	v_mov_b32_e32 v75, v97
	v_mov_b32_e32 v76, 0
	v_mov_b32_e32 v77, v97
	v_mov_b32_e32 v78, v97
	v_mov_b32_e32 v79, v97
	v_mov_b32_e32 v80, 0
	v_mov_b32_e32 v81, v97
	v_mov_b32_e32 v82, v97
	v_mov_b32_e32 v83, v97
	v_mov_b32_e32 v84, 0
	v_mov_b32_e32 v85, v97
	v_mov_b32_e32 v86, v97
	v_mov_b32_e32 v87, v97
	v_mov_b32_e32 v88, 0
	v_mov_b32_e32 v89, v97
	v_mov_b32_e32 v90, v97
	v_mov_b32_e32 v91, v97
	v_mov_b32_e32 v92, 0
	v_mov_b32_e32 v93, v97
	v_mov_b32_e32 v94, v97
	v_mov_b32_e32 v95, v97
	v_mov_b32_e32 v64, 0
	v_mov_b32_e32 v65, v97
	v_mov_b32_e32 v66, v97
	v_mov_b32_e32 v67, v97
	v_mov_b32_e32 v36, 0
	v_mov_b32_e32 v37, v97
	v_mov_b32_e32 v38, v97
	v_mov_b32_e32 v39, v97
	v_mov_b32_e32 v32, 0
	v_mov_b32_e32 v33, v97
	v_mov_b32_e32 v34, v97
	v_mov_b32_e32 v35, v97
	v_mov_b32_e32 v16, 0
	v_mov_b32_e32 v17, v97
	v_mov_b32_e32 v18, v97
	v_mov_b32_e32 v19, v97
	v_mov_b32_e32 v12, 0
	v_mov_b32_e32 v13, v97
	v_mov_b32_e32 v14, v97
	v_mov_b32_e32 v15, v97
	v_mov_b32_e32 v8, 0
	v_mov_b32_e32 v9, v97
	v_mov_b32_e32 v10, v97
	v_mov_b32_e32 v11, v97
	v_mov_b32_e32 v4, 0
	v_mov_b32_e32 v5, v97
	v_mov_b32_e32 v6, v97
	v_mov_b32_e32 v7, v97
	v_mov_b32_e32 v0, 0
	v_mov_b32_e32 v1, v97
	v_mov_b32_e32 v2, v97
	v_mov_b32_e32 v3, v97
	s_waitcnt vmcnt(8)
	s_barrier

.LBB0_889:
	s_lshr_b32 s6, s8, 1
	s_and_b32 s6, s6, 0xf8
	s_or_b32 s6, s6, s2
	s_lshl_b32 s12, s6, 7
	s_lshl_b32 s6, s8, 7
	v_or_b32_e32 v0, s12, v107
	s_and_b32 s13, s6, 0x780
	v_lshlrev_b32_e32 v96, 10, v0
	v_lshl_add_u64 v[102:103], v[98:99], 0, v[96:97]
	v_or_b32_e32 v0, s13, v107
	v_lshlrev_b32_e32 v96, 10, v0
	v_lshl_add_u64 v[104:105], v[100:101], 0, v[96:97]
	v_and_b32_e32 v181, 7, v106
	v_bfe_u32 v180, v106, 3, 3
	v_xor_b32_e32 v180, v181, v180
	v_sub_u32_e32 v180, v180, v181
	v_lshlrev_b32_e32 v180, 4, v180
	v_ashrrev_i32_e32 v181, 31, v180
	v_lshrrev_b32_e32 v186, 6, v106
	v_mov_b32_e32 v187, 0x110
	v_lshl_add_u32 v186, v186, 10, v187
	v_lshl_add_u64 v[188:189], v[102:103], 0, v[180:181]
	v_lshl_add_u64 v[196:197], v[104:105], 0, v[180:181]
	v_readfirstlane_b32 s16, v186
	v_add_co_u32_e32 v190, vcc, s9, v188
	v_addc_co_u32_e32 v191, vcc, 0, v189, vcc
	v_add_co_u32_e32 v192, vcc, s10, v188
	v_addc_co_u32_e32 v193, vcc, 0, v189, vcc
	v_add_co_u32_e32 v194, vcc, s11, v188
	v_addc_co_u32_e32 v195, vcc, 0, v189, vcc
	v_add_co_u32_e32 v198, vcc, s9, v196
	v_addc_co_u32_e32 v199, vcc, 0, v197, vcc
	v_add_co_u32_e32 v200, vcc, s10, v196
	v_addc_co_u32_e32 v201, vcc, 0, v197, vcc
	v_add_co_u32_e32 v202, vcc, s11, v196
	v_addc_co_u32_e32 v203, vcc, 0, v197, vcc
	s_add_u32 m0, s16, 0x0
	s_nop 0
	global_load_lds_dwordx4 v[188:189], off
	s_add_u32 m0, s16, 0x1000
	s_nop 0
	global_load_lds_dwordx4 v[190:191], off
	s_add_u32 m0, s16, 0x2000
	s_nop 0
	global_load_lds_dwordx4 v[192:193], off
	s_add_u32 m0, s16, 0x3000
	s_nop 0
	global_load_lds_dwordx4 v[194:195], off
	s_add_u32 m0, s16, 0x4000
	s_nop 0
	global_load_lds_dwordx4 v[196:197], off
	s_add_u32 m0, s16, 0x5000
	s_nop 0
	global_load_lds_dwordx4 v[198:199], off
	s_add_u32 m0, s16, 0x6000
	s_nop 0
	global_load_lds_dwordx4 v[200:201], off
	s_add_u32 m0, s16, 0x7000
	s_nop 0
	global_load_lds_dwordx4 v[202:203], off
	s_mov_b32 s6, 0x80
	s_add_u32 m0, s16, 0x8000
	v_lshl_add_u64 v[204:205], v[188:189], 0, s[6:7]
	global_load_lds_dwordx4 v[204:205], off
	s_add_u32 m0, s16, 0x9000
	v_lshl_add_u64 v[206:207], v[190:191], 0, s[6:7]
	global_load_lds_dwordx4 v[206:207], off
	s_add_u32 m0, s16, 0xa000
	v_lshl_add_u64 v[204:205], v[192:193], 0, s[6:7]
	global_load_lds_dwordx4 v[204:205], off
	s_add_u32 m0, s16, 0xb000
	v_lshl_add_u64 v[206:207], v[194:195], 0, s[6:7]
	global_load_lds_dwordx4 v[206:207], off
	s_add_u32 m0, s16, 0xc000
	v_lshl_add_u64 v[204:205], v[196:197], 0, s[6:7]
	global_load_lds_dwordx4 v[204:205], off
	s_add_u32 m0, s16, 0xd000
	v_lshl_add_u64 v[206:207], v[198:199], 0, s[6:7]
	global_load_lds_dwordx4 v[206:207], off
	s_add_u32 m0, s16, 0xe000
	v_lshl_add_u64 v[204:205], v[200:201], 0, s[6:7]
	global_load_lds_dwordx4 v[204:205], off
	s_add_u32 m0, s16, 0xf000
	v_lshl_add_u64 v[206:207], v[202:203], 0, s[6:7]
	global_load_lds_dwordx4 v[206:207], off
	s_mov_b32 s15, 0
	s_mov_b32 s14, 0
	v_mov_b32_e32 v28, 0
	v_mov_b32_e32 v29, v97
	v_mov_b32_e32 v30, v97
	v_mov_b32_e32 v31, v97
	v_mov_b32_e32 v36, 0
	v_mov_b32_e32 v37, v97
	v_mov_b32_e32 v38, v97
	v_mov_b32_e32 v39, v97
	v_mov_b32_e32 v40, 0
	v_mov_b32_e32 v41, v97
	v_mov_b32_e32 v42, v97
	v_mov_b32_e32 v43, v97
	v_mov_b32_e32 v60, 0
	v_mov_b32_e32 v61, v97
	v_mov_b32_e32 v62, v97
	v_mov_b32_e32 v63, v97
	v_mov_b32_e32 v80, 0
	v_mov_b32_e32 v81, v97
	v_mov_b32_e32 v82, v97
	v_mov_b32_e32 v83, v97
	v_mov_b32_e32 v84, 0
	v_mov_b32_e32 v85, v97
	v_mov_b32_e32 v86, v97
	v_mov_b32_e32 v87, v97
	v_mov_b32_e32 v88, 0
	v_mov_b32_e32 v89, v97
	v_mov_b32_e32 v90, v97
	v_mov_b32_e32 v91, v97
	v_mov_b32_e32 v92, 0
	v_mov_b32_e32 v93, v97
	v_mov_b32_e32 v94, v97
	v_mov_b32_e32 v95, v97
	v_mov_b32_e32 v32, 0
	v_mov_b32_e32 v33, v97
	v_mov_b32_e32 v34, v97
	v_mov_b32_e32 v35, v97
	v_mov_b32_e32 v24, 0
	v_mov_b32_e32 v25, v97
	v_mov_b32_e32 v26, v97
	v_mov_b32_e32 v27, v97
	v_mov_b32_e32 v20, 0
	v_mov_b32_e32 v21, v97
	v_mov_b32_e32 v22, v97
	v_mov_b32_e32 v23, v97
	v_mov_b32_e32 v16, 0
	v_mov_b32_e32 v17, v97
	v_mov_b32_e32 v18, v97
	v_mov_b32_e32 v19, v97
	v_mov_b32_e32 v12, 0
	v_mov_b32_e32 v13, v97
	v_mov_b32_e32 v14, v97
	v_mov_b32_e32 v15, v97
	v_mov_b32_e32 v8, 0
	v_mov_b32_e32 v9, v97
	v_mov_b32_e32 v10, v97
	v_mov_b32_e32 v11, v97
	v_mov_b32_e32 v4, 0
	v_mov_b32_e32 v5, v97
	v_mov_b32_e32 v6, v97
	v_mov_b32_e32 v7, v97
	v_mov_b32_e32 v0, 0
	v_mov_b32_e32 v1, v97
	v_mov_b32_e32 v2, v97
	v_mov_b32_e32 v3, v97
	s_waitcnt vmcnt(8)
	s_barrier
